# next-phase first weight tile touched into L2 while the seam barrier spins
# baseline (speedup 1.0000x reference)
; __device__ __forceinline__ unsigned xb_add(unsigned* p, unsigned v) { return __hip_atomic_fetch_add(p, v, __ATOMIC_RELAXED, __HIP_MEMORY_SCOPE_AGENT); }
;     __host__ __device__ bool next(int i, Unit& u) const {
;         const long L = (long)i * G + c; if (L >= nwg) return false;
;         int wgid = (int)L; { const int q = nwg / NXCD, r = nwg % NXCD, xcd = wgid % NXCD, off = wgid / NXCD; wgid = (xcd < r ? xcd * (q + 1) : r * (q + 1) + (xcd - r) * q) + off; }
;         const int nig = WGM * nN, gid = wgid / nig, fm = gid * WGM, gsz = (nM - fm) < WGM ? (nM - fm) : WGM;
;         u.pm = fm + ((wgid % nig) % gsz); u.pn = (wgid % nig) / gsz; u.idx = i; return true;
; __device__ __forceinline__ void xcd_local_barrier(unsigned* xl, unsigned x) {
;     asm volatile("s_waitcnt vmcnt(0)" ::: "memory");
;     __syncthreads();
;     if (threadIdx.x == 0) {
;         __builtin_amdgcn_s_waitcnt(0);
;         unsigned* sub = xl + 512 + 64 * x; unsigned* gen = xl + 1024 + 64 * x;
;         const unsigned old = xb_add(sub, 1u), g = old / 32u;
;         if (old + 1u == (g + 1u) * 32u) (void)xb_add(gen, 1u);
.LBB0_668:
	s_and_b64 vcc, exec, s[4:5]
	s_cbranch_vccz .LBB0_692
	s_waitcnt vmcnt(0)
	s_waitcnt vmcnt(0) lgkmcnt(0)
	s_barrier
	s_and_b32 s0, s97, 7
	s_lshr_b32 s1, s97, 3
	s_mulk_i32 s0, 64
	s_add_i32 s0, s0, s1
	s_and_b32 s1, s0, 15
	s_lshr_b32 s1, s1, 2
	s_mul_i32 s1, s1, 0x160000
	s_add_u32 s4, s74, s1
	s_addc_u32 s5, s75, 0
	s_add_u32 s4, s4, 0xc00000
	s_addc_u32 s5, s5, 0
	v_lshrrev_b32_e32 v246, 1, v153
	v_and_b32_e32 v247, 1, v153
	v_mul_u32_u24_e32 v246, 0x1600, v246
	v_lshl_add_u32 v246, v247, 7, v246
	global_load_dword v248, v246, s[4:5]
	s_and_saveexec_b64 s[2:3], s[90:91]
	s_cbranch_execz .LBB0_691
	s_mov_b64 s[4:5], exec
	v_mbcnt_lo_u32_b32 v0, s4, 0
	v_mbcnt_hi_u32_b32 v0, s5, v0
	s_lshl_b32 s0, s92, 6
	v_cmp_eq_u32_e32 vcc, 0, v0
	s_waitcnt vmcnt(0) expcnt(0) lgkmcnt(0)
	s_and_saveexec_b64 s[6:7], vcc
	s_cbranch_execz .LBB0_672
	s_lshl_b32 s1, s0, 2
	s_add_u32 s8, s74, s1
	s_addc_u32 s9, s75, 0
	s_bcnt1_i32_b64 s1, s[4:5]
	v_mov_b32_e32 v1, 0xd000
	v_mov_b32_e32 v2, s1
	global_atomic_add v1, v1, v2, s[8:9] sc0

; __device__ __forceinline__ unsigned xb_add(unsigned* p, unsigned v) { return __hip_atomic_fetch_add(p, v, __ATOMIC_RELAXED, __HIP_MEMORY_SCOPE_AGENT); }
;     __host__ __device__ bool next(int i, Unit& u) const {
;         const long L = (long)i * G + c; if (L >= nwg) return false;
;         int wgid = (int)L; { const int q = nwg / NXCD, r = nwg % NXCD, xcd = wgid % NXCD, off = wgid / NXCD; wgid = (xcd < r ? xcd * (q + 1) : r * (q + 1) + (xcd - r) * q) + off; }
;         const int nig = WGM * nN, gid = wgid / nig, fm = gid * WGM, gsz = (nM - fm) < WGM ? (nM - fm) : WGM;
;         u.pm = fm + ((wgid % nig) % gsz); u.pn = (wgid % nig) / gsz; u.idx = i; return true;
; __device__ __forceinline__ void xcd_local_barrier(unsigned* xl, unsigned x) {
;     asm volatile("s_waitcnt vmcnt(0)" ::: "memory");
;     __syncthreads();
;     if (threadIdx.x == 0) {
;         __builtin_amdgcn_s_waitcnt(0);
;         unsigned* sub = xl + 512 + 64 * x; unsigned* gen = xl + 1024 + 64 * x;
;         const unsigned old = xb_add(sub, 1u), g = old / 32u;
;         if (old + 1u == (g + 1u) * 32u) (void)xb_add(gen, 1u);
.LBB0_793:
	s_and_b64 vcc, exec, s[2:3]
	s_cbranch_vccz .LBB0_817
	s_waitcnt vmcnt(0)
	s_waitcnt vmcnt(0) lgkmcnt(0)
	s_barrier
	s_and_b32 s0, s97, 7
	s_lshr_b32 s1, s97, 3
	s_mulk_i32 s0, 288
	s_add_i32 s0, s0, s1
	s_mul_hi_u32 s1, s0, 0x38e38e4
	s_mulk_i32 s1, 72
	s_sub_i32 s1, s0, s1
	s_lshr_b32 s1, s1, 2
	s_mul_i32 s1, s1, 0x80000
	s_add_u32 s4, s74, s1
	s_addc_u32 s5, s75, 0
	s_add_u32 s4, s4, 0x1200000
	s_addc_u32 s5, s5, 0
	v_lshrrev_b32_e32 v246, 1, v153
	v_and_b32_e32 v247, 1, v153
	v_mul_u32_u24_e32 v246, 0x800, v246
	v_lshl_add_u32 v246, v247, 7, v246
	global_load_dword v248, v246, s[4:5]
	s_and_saveexec_b64 s[2:3], s[90:91]
	s_cbranch_execz .LBB0_816
	s_mov_b64 s[4:5], exec
	v_mbcnt_lo_u32_b32 v0, s4, 0
	v_mbcnt_hi_u32_b32 v0, s5, v0
	s_lshl_b32 s0, s92, 6
	v_cmp_eq_u32_e32 vcc, 0, v0
	s_waitcnt vmcnt(0) expcnt(0) lgkmcnt(0)
	s_and_saveexec_b64 s[6:7], vcc
	s_cbranch_execz .LBB0_797
	s_lshl_b32 s1, s0, 2
	s_add_u32 s10, s74, s1
	s_addc_u32 s11, s75, 0
	s_bcnt1_i32_b64 s1, s[4:5]
	v_mov_b32_e32 v1, 0xd000
	v_mov_b32_e32 v2, s1
	global_atomic_add v1, v1, v2, s[10:11] sc0

; __device__ __forceinline__ unsigned xb_add(unsigned* p, unsigned v) { return __hip_atomic_fetch_add(p, v, __ATOMIC_RELAXED, __HIP_MEMORY_SCOPE_AGENT); }
;     __host__ __device__ bool next(int i, Unit& u) const {
;         const long L = (long)i * G + c; if (L >= nwg) return false;
;         int wgid = (int)L; { const int q = nwg / NXCD, r = nwg % NXCD, xcd = wgid % NXCD, off = wgid / NXCD; wgid = (xcd < r ? xcd * (q + 1) : r * (q + 1) + (xcd - r) * q) + off; }
;         const int nig = WGM * nN, gid = wgid / nig, fm = gid * WGM, gsz = (nM - fm) < WGM ? (nM - fm) : WGM;
;         u.pm = fm + ((wgid % nig) % gsz); u.pn = (wgid % nig) / gsz; u.idx = i; return true;
; __device__ __forceinline__ void xcd_local_barrier(unsigned* xl, unsigned x) {
;     asm volatile("s_waitcnt vmcnt(0)" ::: "memory");
;     __syncthreads();
;     if (threadIdx.x == 0) {
;         __builtin_amdgcn_s_waitcnt(0);
;         unsigned* sub = xl + 512 + 64 * x; unsigned* gen = xl + 1024 + 64 * x;
;         const unsigned old = xb_add(sub, 1u), g = old / 32u;
;         if (old + 1u == (g + 1u) * 32u) (void)xb_add(gen, 1u);
.LBB0_1308:
	s_and_b64 vcc, exec, s[2:3]
	s_cbranch_vccz .LBB0_1332
	s_waitcnt vmcnt(0)
	s_barrier
	s_and_b32 s0, s97, 7
	s_lshr_b32 s1, s97, 3
	s_mulk_i32 s0, 64
	s_add_i32 s0, s0, s1
	s_and_b32 s1, s0, 15
	s_lshr_b32 s1, s1, 2
	s_mul_i32 s1, s1, 0x80000
	s_add_u32 s4, s74, s1
	s_addc_u32 s5, s75, 0
	s_add_u32 s4, s4, 0x1b00000
	s_addc_u32 s5, s5, 0
	v_lshrrev_b32_e32 v246, 1, v153
	v_and_b32_e32 v247, 1, v153
	v_mul_u32_u24_e32 v246, 0x800, v246
	v_lshl_add_u32 v246, v247, 7, v246
	global_load_dword v248, v246, s[4:5]
	s_and_saveexec_b64 s[2:3], s[90:91]
	s_cbranch_execz .LBB0_1331
	s_mov_b64 s[4:5], exec
	v_mbcnt_lo_u32_b32 v0, s4, 0
	v_mbcnt_hi_u32_b32 v0, s5, v0
	s_lshl_b32 s0, s92, 6
	v_cmp_eq_u32_e32 vcc, 0, v0
	s_waitcnt vmcnt(0) expcnt(0) lgkmcnt(0)
	s_and_saveexec_b64 s[6:7], vcc
	s_cbranch_execz .LBB0_1312
	s_lshl_b32 s1, s0, 2
	s_add_u32 s8, s74, s1
	s_addc_u32 s9, s75, 0
	s_bcnt1_i32_b64 s1, s[4:5]
	v_mov_b32_e32 v1, 0xd000
	v_mov_b32_e32 v2, s1
	global_atomic_add v1, v1, v2, s[8:9] sc0

; __device__ __forceinline__ unsigned xb_add(unsigned* p, unsigned v) { return __hip_atomic_fetch_add(p, v, __ATOMIC_RELAXED, __HIP_MEMORY_SCOPE_AGENT); }
;     __host__ __device__ bool next(int i, Unit& u) const {
;         const long L = (long)i * G + c; if (L >= nwg) return false;
;         int wgid = (int)L; { const int q = nwg / NXCD, r = nwg % NXCD, xcd = wgid % NXCD, off = wgid / NXCD; wgid = (xcd < r ? xcd * (q + 1) : r * (q + 1) + (xcd - r) * q) + off; }
;         const int nig = WGM * nN, gid = wgid / nig, fm = gid * WGM, gsz = (nM - fm) < WGM ? (nM - fm) : WGM;
;         u.pm = fm + ((wgid % nig) % gsz); u.pn = (wgid % nig) / gsz; u.idx = i; return true;
; __device__ __forceinline__ void xcd_local_barrier(unsigned* xl, unsigned x) {
;     asm volatile("s_waitcnt vmcnt(0)" ::: "memory");
;     __syncthreads();
;     if (threadIdx.x == 0) {
;         __builtin_amdgcn_s_waitcnt(0);
;         unsigned* sub = xl + 512 + 64 * x; unsigned* gen = xl + 1024 + 64 * x;
;         const unsigned old = xb_add(sub, 1u), g = old / 32u;
;         if (old + 1u == (g + 1u) * 32u) (void)xb_add(gen, 1u);
.LBB0_1413:
	s_and_b64 vcc, exec, s[2:3]
	s_cbranch_vccz .LBB0_1437
	s_waitcnt vmcnt(0)
	s_barrier
	s_and_b32 s0, s97, 7
	s_lshr_b32 s1, s97, 3
	s_mulk_i32 s0, 64
	s_add_i32 s0, s0, s1
	s_and_b32 s1, s0, 15
	s_lshr_b32 s1, s1, 2
	s_mul_i32 s1, s1, 0x80000
	s_add_u32 s4, s74, s1
	s_addc_u32 s5, s75, 0
	s_add_u32 s4, s4, 0x1d00000
	s_addc_u32 s5, s5, 0
	v_lshrrev_b32_e32 v246, 1, v153
	v_and_b32_e32 v247, 1, v153
	v_mul_u32_u24_e32 v246, 0x800, v246
	v_lshl_add_u32 v246, v247, 7, v246
	global_load_dword v248, v246, s[4:5]
	s_and_saveexec_b64 s[2:3], s[90:91]
	s_cbranch_execz .LBB0_1436
	s_mov_b64 s[4:5], exec
	v_mbcnt_lo_u32_b32 v0, s4, 0
	v_mbcnt_hi_u32_b32 v0, s5, v0
	s_lshl_b32 s0, s92, 6
	v_cmp_eq_u32_e32 vcc, 0, v0
	s_waitcnt vmcnt(0) expcnt(0) lgkmcnt(0)
	s_and_saveexec_b64 s[6:7], vcc
	s_cbranch_execz .LBB0_1417
	s_lshl_b32 s1, s0, 2
	s_add_u32 s8, s74, s1
	s_addc_u32 s9, s75, 0
	s_bcnt1_i32_b64 s1, s[4:5]
	v_mov_b32_e32 v1, 0xd000
	v_mov_b32_e32 v2, s1
	global_atomic_add v1, v1, v2, s[8:9] sc0

; __device__ __forceinline__ unsigned xb_add(unsigned* p, unsigned v) { return __hip_atomic_fetch_add(p, v, __ATOMIC_RELAXED, __HIP_MEMORY_SCOPE_AGENT); }
;     __host__ __device__ bool next(int i, Unit& u) const {
;         const long L = (long)i * G + c; if (L >= nwg) return false;
;         int wgid = (int)L; { const int q = nwg / NXCD, r = nwg % NXCD, xcd = wgid % NXCD, off = wgid / NXCD; wgid = (xcd < r ? xcd * (q + 1) : r * (q + 1) + (xcd - r) * q) + off; }
;         const int nig = WGM * nN, gid = wgid / nig, fm = gid * WGM, gsz = (nM - fm) < WGM ? (nM - fm) : WGM;
;         u.pm = fm + ((wgid % nig) % gsz); u.pn = (wgid % nig) / gsz; u.idx = i; return true;
; __device__ __forceinline__ void xcd_local_barrier(unsigned* xl, unsigned x) {
;     asm volatile("s_waitcnt vmcnt(0)" ::: "memory");
;     __syncthreads();
;     if (threadIdx.x == 0) {
;         __builtin_amdgcn_s_waitcnt(0);
;         unsigned* sub = xl + 512 + 64 * x; unsigned* gen = xl + 1024 + 64 * x;
;         const unsigned old = xb_add(sub, 1u), g = old / 32u;
;         if (old + 1u == (g + 1u) * 32u) (void)xb_add(gen, 1u);
.LBB0_1534:
	s_and_b64 vcc, exec, s[2:3]
	s_cbranch_vccz .LBB0_1558
	s_waitcnt vmcnt(0)
	s_waitcnt lgkmcnt(0)
	s_barrier
	s_and_b32 s0, s97, 7
	s_lshr_b32 s1, s97, 3
	s_mulk_i32 s0, 352
	s_add_i32 s0, s0, s1
	s_mul_hi_u32 s1, s0, 0x2e8ba2f
	s_mulk_i32 s1, 88
	s_sub_i32 s1, s0, s1
	s_lshr_b32 s1, s1, 2
	s_mul_i32 s1, s1, 0x80000
	s_add_u32 s4, s74, s1
	s_addc_u32 s5, s75, 0
	s_add_u32 s4, s4, 0x1f00000
	s_addc_u32 s5, s5, 0
	v_lshrrev_b32_e32 v246, 1, v153
	v_and_b32_e32 v247, 1, v153
	v_mul_u32_u24_e32 v246, 0x800, v246
	v_lshl_add_u32 v246, v247, 7, v246
	global_load_dword v248, v246, s[4:5]
	s_and_saveexec_b64 s[2:3], s[90:91]
	s_cbranch_execz .LBB0_1557
	s_mov_b64 s[4:5], exec
	v_mbcnt_lo_u32_b32 v0, s4, 0
	v_mbcnt_hi_u32_b32 v0, s5, v0
	s_lshl_b32 s0, s92, 6
	v_cmp_eq_u32_e32 vcc, 0, v0
	s_waitcnt vmcnt(0) expcnt(0) lgkmcnt(0)
	s_and_saveexec_b64 s[8:9], vcc
	s_cbranch_execz .LBB0_1538
	s_lshl_b32 s1, s0, 2
	s_add_u32 s10, s74, s1
	s_addc_u32 s11, s75, 0
	s_bcnt1_i32_b64 s1, s[4:5]
	v_mov_b32_e32 v1, 0xd000
	v_mov_b32_e32 v2, s1
	global_atomic_add v1, v1, v2, s[10:11] sc0

; __device__ __forceinline__ unsigned xb_add(unsigned* p, unsigned v) { return __hip_atomic_fetch_add(p, v, __ATOMIC_RELAXED, __HIP_MEMORY_SCOPE_AGENT); }
;     __host__ __device__ bool next(int i, Unit& u) const {
;         const long L = (long)i * G + c; if (L >= nwg) return false;
;         int wgid = (int)L; { const int q = nwg / NXCD, r = nwg % NXCD, xcd = wgid % NXCD, off = wgid / NXCD; wgid = (xcd < r ? xcd * (q + 1) : r * (q + 1) + (xcd - r) * q) + off; }
;         const int nig = WGM * nN, gid = wgid / nig, fm = gid * WGM, gsz = (nM - fm) < WGM ? (nM - fm) : WGM;
;         u.pm = fm + ((wgid % nig) % gsz); u.pn = (wgid % nig) / gsz; u.idx = i; return true;
; __device__ __forceinline__ void xcd_local_barrier(unsigned* xl, unsigned x) {
;     asm volatile("s_waitcnt vmcnt(0)" ::: "memory");
;     __syncthreads();
;     if (threadIdx.x == 0) {
;         __builtin_amdgcn_s_waitcnt(0);
;         unsigned* sub = xl + 512 + 64 * x; unsigned* gen = xl + 1024 + 64 * x;
;         const unsigned old = xb_add(sub, 1u), g = old / 32u;
;         if (old + 1u == (g + 1u) * 32u) (void)xb_add(gen, 1u);
.LBB0_1674:
	s_and_b64 vcc, exec, s[2:3]
	s_cbranch_vccz .LBB0_1698
	s_waitcnt vmcnt(0)
	s_waitcnt vmcnt(0) lgkmcnt(0)
	s_barrier
	s_and_b32 s0, s97, 7
	s_lshr_b32 s1, s97, 3
	s_mulk_i32 s0, 64
	s_add_i32 s0, s0, s1
	s_and_b32 s1, s0, 15
	s_lshr_b32 s1, s1, 2
	s_mul_i32 s1, s1, 0x160000
	s_add_u32 s4, s74, s1
	s_addc_u32 s5, s75, 0
	s_add_u32 s4, s4, 0x2a00000
	s_addc_u32 s5, s5, 0
	v_lshrrev_b32_e32 v246, 1, v153
	v_and_b32_e32 v247, 1, v153
	v_mul_u32_u24_e32 v246, 0x1600, v246
	v_lshl_add_u32 v246, v247, 7, v246
	global_load_dword v248, v246, s[4:5]
	s_and_saveexec_b64 s[2:3], s[90:91]
	s_cbranch_execz .LBB0_1697
	s_mov_b64 s[0:1], exec
	v_mbcnt_lo_u32_b32 v0, s0, 0
	v_mbcnt_hi_u32_b32 v0, s1, v0
	s_lshl_b32 s6, s92, 6
	v_cmp_eq_u32_e32 vcc, 0, v0
	s_waitcnt vmcnt(0) expcnt(0) lgkmcnt(0)
	s_and_saveexec_b64 s[4:5], vcc
	s_cbranch_execz .LBB0_1678
	s_lshl_b32 s7, s6, 2
	s_add_u32 s8, s74, s7
	s_addc_u32 s9, s75, 0
	s_bcnt1_i32_b64 s0, s[0:1]
	v_mov_b32_e32 v1, 0xd000
	v_mov_b32_e32 v2, s0
	global_atomic_add v1, v1, v2, s[8:9] sc0
